# hand-written WKV scan block (prefetched LDS operands, deferred y transpose-reduce) + de-serialized retention LOADQK prefetch
# speedup vs baseline: 1.1724x; 1.1724x over previous
.LBB0_2454:
	s_cmp_lg_u32 s5, 16
	s_cselect_b64 s[80:81], -1, 0
	s_cmp_eq_u32 s5, 16
	s_waitcnt vmcnt(6)
	v_cndmask_b32_e64 v97, 0, v97, s[54:55]
	v_cndmask_b32_e64 v96, 0, v96, s[54:55]
	v_cndmask_b32_e64 v95, 0, v95, s[54:55]
	v_cndmask_b32_e64 v94, 0, v94, s[54:55]
	v_cndmask_b32_e64 v101, 0, v101, s[54:55]
	v_cndmask_b32_e64 v100, 0, v100, s[54:55]
	v_cndmask_b32_e64 v99, 0, v99, s[54:55]
	v_cndmask_b32_e64 v98, 0, v98, s[54:55]
	s_waitcnt vmcnt(4)
	v_cndmask_b32_e64 v105, 0, v105, s[58:59]
	v_cndmask_b32_e64 v104, 0, v104, s[58:59]
	v_cndmask_b32_e64 v103, 0, v103, s[58:59]
	v_cndmask_b32_e64 v102, 0, v102, s[58:59]
	v_cndmask_b32_e64 v109, 0, v109, s[58:59]
	v_cndmask_b32_e64 v108, 0, v108, s[58:59]
	v_cndmask_b32_e64 v107, 0, v107, s[58:59]
	v_cndmask_b32_e64 v106, 0, v106, s[58:59]
	s_waitcnt vmcnt(2)
	v_cndmask_b32_e64 v113, 0, v113, s[60:61]
	v_cndmask_b32_e64 v112, 0, v112, s[60:61]
	v_cndmask_b32_e64 v111, 0, v111, s[60:61]
	v_cndmask_b32_e64 v110, 0, v110, s[60:61]
	v_cndmask_b32_e64 v117, 0, v117, s[60:61]
	v_cndmask_b32_e64 v116, 0, v116, s[60:61]
	v_cndmask_b32_e64 v115, 0, v115, s[60:61]
	v_cndmask_b32_e64 v114, 0, v114, s[60:61]
	s_waitcnt vmcnt(0)
	v_cndmask_b32_e64 v121, 0, v121, s[62:63]
	v_cndmask_b32_e64 v120, 0, v120, s[62:63]
	v_cndmask_b32_e64 v119, 0, v119, s[62:63]
	v_cndmask_b32_e64 v118, 0, v118, s[62:63]
	v_cndmask_b32_e64 v125, 0, v125, s[62:63]
	v_cndmask_b32_e64 v124, 0, v124, s[62:63]
	v_cndmask_b32_e64 v123, 0, v123, s[62:63]
	v_cndmask_b32_e64 v122, 0, v122, s[62:63]
	ds_write_b128 v241, v[98:101]
	ds_write_b128 v241, v[94:97] offset:34816
	ds_write_b128 v242, v[106:109]
	ds_write_b128 v242, v[102:105] offset:34816
	ds_write_b128 v243, v[114:117]
	ds_write_b128 v243, v[110:113] offset:34816
	ds_write_b128 v244, v[122:125]
	ds_write_b128 v244, v[118:121] offset:34816
	s_cbranch_scc1 .LBB0_2456
	v_cmp_gt_i32_e32 vcc, s23, v155
	s_or_b32 s38, s65, 16
	s_lshl_b32 s39, s65, 1
	v_cndmask_b32_e32 v86, 0, v155, vcc
	v_add_u32_e32 v86, s38, v86
	v_ashrrev_i32_e32 v87, 31, v86
	v_lshlrev_b64 v[90:91], 11, v[86:87]
	v_or_b32_e32 v90, v90, v154
	v_lshl_add_u64 v[86:87], s[12:13], 0, v[90:91]
	v_lshl_add_u64 v[90:91], s[18:19], 0, v[90:91]
	global_load_dwordx4 v[98:101], v[86:87], off
	s_add_u32 s54, s72, s39
	global_load_dwordx4 v[94:97], v[90:91], off
	s_addc_u32 s55, s73, 0
	v_cmp_gt_i32_e32 vcc, s23, v156
	s_nop 1
	v_cndmask_b32_e32 v86, 0, v156, vcc
	v_add_u32_e32 v86, s38, v86
	v_ashrrev_i32_e32 v87, 31, v86
	v_lshlrev_b64 v[90:91], 11, v[86:87]
	v_or_b32_e32 v90, v90, v154
	v_lshl_add_u64 v[86:87], s[12:13], 0, v[90:91]
	v_lshl_add_u64 v[90:91], s[18:19], 0, v[90:91]
	global_load_dwordx4 v[106:109], v[86:87], off
	global_load_dwordx4 v[102:105], v[90:91], off
	v_cmp_gt_i32_e32 vcc, s23, v240
	s_nop 1
	v_cndmask_b32_e32 v86, 0, v240, vcc
	v_add_u32_e32 v86, s38, v86
	v_ashrrev_i32_e32 v87, 31, v86
	v_lshlrev_b64 v[90:91], 11, v[86:87]
	v_or_b32_e32 v90, v90, v154
	v_lshl_add_u64 v[86:87], s[12:13], 0, v[90:91]
	v_lshl_add_u64 v[90:91], s[18:19], 0, v[90:91]
	global_load_dwordx4 v[114:117], v[86:87], off
	global_load_dwordx4 v[110:113], v[90:91], off
	v_cmp_gt_i32_e32 vcc, s23, v239
	s_nop 1
	v_cndmask_b32_e32 v86, 0, v239, vcc
	v_add_u32_e32 v86, s38, v86
	v_ashrrev_i32_e32 v87, 31, v86
	v_lshlrev_b64 v[90:91], 11, v[86:87]
	v_or_b32_e32 v90, v90, v154
	v_lshl_add_u64 v[86:87], s[12:13], 0, v[90:91]
	v_lshl_add_u64 v[90:91], s[18:19], 0, v[90:91]
	global_load_dwordx4 v[122:125], v[86:87], off
	global_load_dwordx4 v[118:121], v[90:91], off
	v_mov_b64_e32 v[90:91], s[54:55]
	v_mad_i64_i32 v[86:87], s[38:39], v155, s9, v[90:91]
	v_mov_b32_e32 v155, v81
	v_mad_i64_i32 v[90:91], s[38:39], v156, s9, v[90:91]
	v_lshl_add_u64 v[86:87], v[86:87], 0, v[154:155]
	v_lshl_add_u64 v[90:91], v[90:91], 0, v[154:155]
	global_load_dwordx4 v[86:89], v[86:87], off offset:32
	s_nop 0
	global_load_dwordx4 v[90:93], v[90:91], off offset:32

.LBB0_4096:
	v_readlane_b32 s4, v252, 22
	v_readlane_b32 s5, v252, 23
	v_mov_b32_e32 v0, v226
	s_andn2_b64 vcc, exec, s[4:5]
	s_cbranch_vccnz .LBB0_4095
	s_movk_i32 s4, 0x100
	v_and_b32_e32 v33, 15, v0
	v_cmp_gt_i32_e64 s[42:43], s4, v0
	v_ashrrev_i32_e32 v35, 5, v0
	v_and_b32_e32 v51, 31, v0
	v_lshrrev_b32_e32 v1, 3, v0
	v_readlane_b32 s44, v255, 12
	v_bfe_u32 v0, v0, 4, 4
	v_readlane_b32 s4, v254, 49
	v_lshlrev_b32_e32 v80, 3, v51
	v_readlane_b32 s45, v255, 13
	v_readlane_b32 s46, v255, 14
	v_readlane_b32 s47, v255, 15
	v_readlane_b32 s48, v255, 16
	v_readlane_b32 s49, v255, 17
	v_lshl_add_u32 v76, v0, 3, s4
	v_readlane_b32 s4, v254, 4
	v_lshlrev_b32_e32 v34, 1, v51
	v_readlane_b32 s50, v255, 18
	v_readlane_b32 s51, v255, 19
	v_lshl_add_u64 v[36:37], s[48:49], 0, v[80:81]
	v_lshl_add_u64 v[38:39], s[44:45], 0, v[80:81]
	v_lshl_add_u64 v[40:41], s[46:47], 0, v[80:81]
	v_lshlrev_b32_e32 v80, 4, v33
	v_readlane_b32 s5, v254, 5
	v_lshlrev_b32_e32 v0, 7, v0
	v_and_b32_e32 v53, 30, v1
	v_lshlrev_b32_e32 v32, 2, v33
	v_lshl_or_b32 v74, v35, 6, v34
	v_and_b32_e32 v1, 1, v33
	v_cmp_ne_u32_e64 s[44:45], 0, v1
	v_and_b32_e32 v1, 2, v33
	v_cmp_ne_u32_e64 s[46:47], 0, v1
	v_cmp_eq_u32_e64 s[48:49], 2, v33
	v_cmp_eq_u32_e64 s[50:51], 3, v33
	v_cmp_eq_u32_e64 s[52:53], 4, v33
	v_cmp_eq_u32_e64 s[54:55], 5, v33
	v_cmp_eq_u32_e64 s[56:57], 6, v33
	v_cmp_eq_u32_e64 s[58:59], 7, v33
	v_cmp_eq_u32_e64 s[60:61], 8, v33
	v_cmp_eq_u32_e64 s[62:63], 9, v33
	v_cmp_eq_u32_e64 s[64:65], 10, v33
	v_cmp_eq_u32_e64 s[66:67], 11, v33
	v_cmp_eq_u32_e64 s[68:69], 12, v33
	v_cmp_eq_u32_e64 s[70:71], 13, v33
	v_cmp_eq_u32_e64 s[72:73], 14, v33
	v_cmp_eq_u32_e64 s[74:75], 15, v33
	v_lshlrev_b32_e32 v75, 8, v33
	v_lshl_add_u64 v[42:43], s[4:5], 0, v[80:81]
	v_lshlrev_b32_e32 v77, 2, v0
	s_mov_b32 s7, s2
	s_branch .LBB0_4099

.LBB0_4117:
	s_and_b64 vcc, exec, s[38:39]
	s_cbranch_vccz .LBB0_4106
	v_lshl_add_u32 v104, v78, 2, s84
	ds_read_b128 v[20:23], v83 offset:4096
	ds_read_b128 v[16:19], v83 offset:0
	ds_read_b128 v[28:31], v83 offset:12288
	ds_read_b64 v[88:89], v104 offset:20480
	ds_read_b128 v[24:27], v83 offset:8192
	s_waitcnt lgkmcnt(4)
	v_pk_mul_f32 v[90:91], v[0:1], v[20:21] op_sel_hi:[1,0]
	v_pk_fma_f32 v[90:91], v[2:3], v[20:21], v[90:91] op_sel:[0,1,0]
	v_pk_fma_f32 v[90:91], v[4:5], v[22:23], v[90:91] op_sel_hi:[1,0,1]
	v_pk_fma_f32 v[90:91], v[6:7], v[22:23], v[90:91] op_sel:[0,1,0]
	ds_read_b128 v[20:23], v83 offset:4352
	ds_read_b128 v[84:87], v83 offset:16384
	v_add_f32_dpp v90, v90, v90 quad_perm:[1,0,3,2] row_mask:0xf bank_mask:0xf bound_ctrl:1
	v_add_f32_dpp v91, v91, v91 quad_perm:[1,0,3,2] row_mask:0xf bank_mask:0xf bound_ctrl:1
	s_nop 0
	v_add_f32_dpp v90, v90, v90 quad_perm:[2,3,0,1] row_mask:0xf bank_mask:0xf bound_ctrl:1
	v_add_f32_dpp v91, v91, v91 quad_perm:[2,3,0,1] row_mask:0xf bank_mask:0xf bound_ctrl:1
	s_nop 0
	v_add_f32_dpp v90, v90, v90 row_half_mirror row_mask:0xf bank_mask:0xf bound_ctrl:1
	v_add_f32_dpp v91, v91, v91 row_half_mirror row_mask:0xf bank_mask:0xf bound_ctrl:1
	s_nop 0
	v_add_f32_dpp v90, v90, v90 row_mirror row_mask:0xf bank_mask:0xf bound_ctrl:1
	v_add_f32_dpp v91, v91, v91 row_mirror row_mask:0xf bank_mask:0xf bound_ctrl:1
	s_waitcnt lgkmcnt(2)
	v_pk_mul_f32 v[0:1], v[0:1], v[16:17] op_sel_hi:[1,0]
	v_pk_mul_f32 v[2:3], v[2:3], v[16:17] op_sel:[0,1]
	v_pk_mul_f32 v[4:5], v[4:5], v[18:19] op_sel_hi:[1,0]
	v_pk_mul_f32 v[6:7], v[6:7], v[18:19] op_sel:[0,1]
	ds_read_b128 v[16:19], v83 offset:256
	v_pk_fma_f32 v[0:1], v[88:89], v[28:29], v[0:1] op_sel_hi:[1,0,1]
	v_pk_fma_f32 v[2:3], v[88:89], v[28:29], v[2:3] op_sel:[0,1,0]
	v_pk_fma_f32 v[4:5], v[88:89], v[30:31], v[4:5] op_sel_hi:[1,0,1]
	v_pk_fma_f32 v[6:7], v[88:89], v[30:31], v[6:7] op_sel:[0,1,0]
	ds_read_b128 v[28:31], v83 offset:12544
	ds_read_b64 v[88:89], v104 offset:20736
	v_pk_fma_f32 v[0:1], v[90:91], v[24:25], v[0:1] op_sel_hi:[1,0,1] neg_lo:[1,0,0] neg_hi:[1,0,0]
	v_pk_fma_f32 v[2:3], v[90:91], v[24:25], v[2:3] op_sel:[0,1,0] neg_lo:[1,0,0] neg_hi:[1,0,0]
	v_pk_fma_f32 v[4:5], v[90:91], v[26:27], v[4:5] op_sel_hi:[1,0,1] neg_lo:[1,0,0] neg_hi:[1,0,0]
	v_pk_fma_f32 v[6:7], v[90:91], v[26:27], v[6:7] op_sel:[0,1,0] neg_lo:[1,0,0] neg_hi:[1,0,0]
	ds_read_b128 v[24:27], v83 offset:8448
	s_waitcnt lgkmcnt(4)
	v_pk_mul_f32 v[90:91], v[0:1], v[20:21] op_sel_hi:[1,0]
	v_pk_mul_f32 v[92:93], v[0:1], v[84:85] op_sel_hi:[1,0]
	v_pk_fma_f32 v[90:91], v[2:3], v[20:21], v[90:91] op_sel:[0,1,0]
	v_pk_fma_f32 v[92:93], v[2:3], v[84:85], v[92:93] op_sel:[0,1,0]
	v_pk_fma_f32 v[90:91], v[4:5], v[22:23], v[90:91] op_sel_hi:[1,0,1]
	v_pk_fma_f32 v[92:93], v[4:5], v[86:87], v[92:93] op_sel_hi:[1,0,1]
	v_pk_fma_f32 v[90:91], v[6:7], v[22:23], v[90:91] op_sel:[0,1,0]
	v_pk_fma_f32 v[8:9], v[6:7], v[86:87], v[92:93] op_sel:[0,1,0]
	ds_read_b128 v[20:23], v83 offset:4608
	ds_read_b128 v[84:87], v83 offset:16640
	v_add_f32_dpp v90, v90, v90 quad_perm:[1,0,3,2] row_mask:0xf bank_mask:0xf bound_ctrl:1
	v_add_f32_dpp v91, v91, v91 quad_perm:[1,0,3,2] row_mask:0xf bank_mask:0xf bound_ctrl:1
	s_nop 0
	v_add_f32_dpp v90, v90, v90 quad_perm:[2,3,0,1] row_mask:0xf bank_mask:0xf bound_ctrl:1
	v_add_f32_dpp v91, v91, v91 quad_perm:[2,3,0,1] row_mask:0xf bank_mask:0xf bound_ctrl:1
	s_nop 0
	v_add_f32_dpp v90, v90, v90 row_half_mirror row_mask:0xf bank_mask:0xf bound_ctrl:1
	v_add_f32_dpp v91, v91, v91 row_half_mirror row_mask:0xf bank_mask:0xf bound_ctrl:1
	s_nop 0
	v_add_f32_dpp v90, v90, v90 row_mirror row_mask:0xf bank_mask:0xf bound_ctrl:1
	v_add_f32_dpp v91, v91, v91 row_mirror row_mask:0xf bank_mask:0xf bound_ctrl:1
	s_waitcnt lgkmcnt(2)
	v_pk_mul_f32 v[0:1], v[0:1], v[16:17] op_sel_hi:[1,0]
	v_pk_mul_f32 v[2:3], v[2:3], v[16:17] op_sel:[0,1]
	v_pk_mul_f32 v[4:5], v[4:5], v[18:19] op_sel_hi:[1,0]
	v_pk_mul_f32 v[6:7], v[6:7], v[18:19] op_sel:[0,1]
	ds_read_b128 v[16:19], v83 offset:512
	v_pk_fma_f32 v[0:1], v[88:89], v[28:29], v[0:1] op_sel_hi:[1,0,1]
	v_pk_fma_f32 v[2:3], v[88:89], v[28:29], v[2:3] op_sel:[0,1,0]
	v_pk_fma_f32 v[4:5], v[88:89], v[30:31], v[4:5] op_sel_hi:[1,0,1]
	v_pk_fma_f32 v[6:7], v[88:89], v[30:31], v[6:7] op_sel:[0,1,0]
	ds_read_b128 v[28:31], v83 offset:12800
	ds_read_b64 v[88:89], v104 offset:20992
	v_pk_fma_f32 v[0:1], v[90:91], v[24:25], v[0:1] op_sel_hi:[1,0,1] neg_lo:[1,0,0] neg_hi:[1,0,0]
	v_pk_fma_f32 v[2:3], v[90:91], v[24:25], v[2:3] op_sel:[0,1,0] neg_lo:[1,0,0] neg_hi:[1,0,0]
	v_pk_fma_f32 v[4:5], v[90:91], v[26:27], v[4:5] op_sel_hi:[1,0,1] neg_lo:[1,0,0] neg_hi:[1,0,0]
	v_pk_fma_f32 v[6:7], v[90:91], v[26:27], v[6:7] op_sel:[0,1,0] neg_lo:[1,0,0] neg_hi:[1,0,0]
	ds_read_b128 v[24:27], v83 offset:8704
	s_waitcnt lgkmcnt(4)
	v_pk_mul_f32 v[90:91], v[0:1], v[20:21] op_sel_hi:[1,0]
	v_pk_mul_f32 v[92:93], v[0:1], v[84:85] op_sel_hi:[1,0]
	v_pk_fma_f32 v[90:91], v[2:3], v[20:21], v[90:91] op_sel:[0,1,0]
	v_pk_fma_f32 v[92:93], v[2:3], v[84:85], v[92:93] op_sel:[0,1,0]
	v_pk_fma_f32 v[90:91], v[4:5], v[22:23], v[90:91] op_sel_hi:[1,0,1]
	v_pk_fma_f32 v[92:93], v[4:5], v[86:87], v[92:93] op_sel_hi:[1,0,1]
	v_pk_fma_f32 v[90:91], v[6:7], v[22:23], v[90:91] op_sel:[0,1,0]
	v_pk_fma_f32 v[10:11], v[6:7], v[86:87], v[92:93] op_sel:[0,1,0]
	ds_read_b128 v[20:23], v83 offset:4864
	ds_read_b128 v[84:87], v83 offset:16896
	v_add_f32_dpp v90, v90, v90 quad_perm:[1,0,3,2] row_mask:0xf bank_mask:0xf bound_ctrl:1
	v_add_f32_dpp v91, v91, v91 quad_perm:[1,0,3,2] row_mask:0xf bank_mask:0xf bound_ctrl:1
	v_add_f32_dpp v8, v8, v8 row_mirror row_mask:0xf bank_mask:0x3
	v_add_f32_dpp v90, v90, v90 quad_perm:[2,3,0,1] row_mask:0xf bank_mask:0xf bound_ctrl:1
	v_add_f32_dpp v91, v91, v91 quad_perm:[2,3,0,1] row_mask:0xf bank_mask:0xf bound_ctrl:1
	v_add_f32_dpp v9, v9, v9 row_mirror row_mask:0xf bank_mask:0x3
	v_add_f32_dpp v90, v90, v90 row_half_mirror row_mask:0xf bank_mask:0xf bound_ctrl:1
	v_add_f32_dpp v91, v91, v91 row_half_mirror row_mask:0xf bank_mask:0xf bound_ctrl:1
	v_add_f32_dpp v8, v10, v10 row_mirror row_mask:0xf bank_mask:0xc
	v_add_f32_dpp v90, v90, v90 row_mirror row_mask:0xf bank_mask:0xf bound_ctrl:1
	v_add_f32_dpp v91, v91, v91 row_mirror row_mask:0xf bank_mask:0xf bound_ctrl:1
	s_waitcnt lgkmcnt(2)
	v_pk_mul_f32 v[0:1], v[0:1], v[16:17] op_sel_hi:[1,0]
	v_pk_mul_f32 v[2:3], v[2:3], v[16:17] op_sel:[0,1]
	v_pk_mul_f32 v[4:5], v[4:5], v[18:19] op_sel_hi:[1,0]
	v_pk_mul_f32 v[6:7], v[6:7], v[18:19] op_sel:[0,1]
	ds_read_b128 v[16:19], v83 offset:768
	v_pk_fma_f32 v[0:1], v[88:89], v[28:29], v[0:1] op_sel_hi:[1,0,1]
	v_pk_fma_f32 v[2:3], v[88:89], v[28:29], v[2:3] op_sel:[0,1,0]
	v_pk_fma_f32 v[4:5], v[88:89], v[30:31], v[4:5] op_sel_hi:[1,0,1]
	v_pk_fma_f32 v[6:7], v[88:89], v[30:31], v[6:7] op_sel:[0,1,0]
	ds_read_b128 v[28:31], v83 offset:13056
	ds_read_b64 v[88:89], v104 offset:21248
	v_pk_fma_f32 v[0:1], v[90:91], v[24:25], v[0:1] op_sel_hi:[1,0,1] neg_lo:[1,0,0] neg_hi:[1,0,0]
	v_pk_fma_f32 v[2:3], v[90:91], v[24:25], v[2:3] op_sel:[0,1,0] neg_lo:[1,0,0] neg_hi:[1,0,0]
	v_pk_fma_f32 v[4:5], v[90:91], v[26:27], v[4:5] op_sel_hi:[1,0,1] neg_lo:[1,0,0] neg_hi:[1,0,0]
	v_pk_fma_f32 v[6:7], v[90:91], v[26:27], v[6:7] op_sel:[0,1,0] neg_lo:[1,0,0] neg_hi:[1,0,0]
	ds_read_b128 v[24:27], v83 offset:8960
	v_add_f32_dpp v9, v11, v11 row_mirror row_mask:0xf bank_mask:0xc
	s_waitcnt lgkmcnt(4)
	v_pk_mul_f32 v[90:91], v[0:1], v[20:21] op_sel_hi:[1,0]
	v_pk_mul_f32 v[92:93], v[0:1], v[84:85] op_sel_hi:[1,0]
	v_pk_fma_f32 v[90:91], v[2:3], v[20:21], v[90:91] op_sel:[0,1,0]
	v_pk_fma_f32 v[92:93], v[2:3], v[84:85], v[92:93] op_sel:[0,1,0]
	v_pk_fma_f32 v[90:91], v[4:5], v[22:23], v[90:91] op_sel_hi:[1,0,1]
	v_pk_fma_f32 v[92:93], v[4:5], v[86:87], v[92:93] op_sel_hi:[1,0,1]
	v_pk_fma_f32 v[90:91], v[6:7], v[22:23], v[90:91] op_sel:[0,1,0]
	v_pk_fma_f32 v[12:13], v[6:7], v[86:87], v[92:93] op_sel:[0,1,0]
	ds_read_b128 v[20:23], v83 offset:5120
	ds_read_b128 v[84:87], v83 offset:17152
	v_add_f32_dpp v90, v90, v90 quad_perm:[1,0,3,2] row_mask:0xf bank_mask:0xf bound_ctrl:1
	v_add_f32_dpp v91, v91, v91 quad_perm:[1,0,3,2] row_mask:0xf bank_mask:0xf bound_ctrl:1
	s_nop 0
	v_add_f32_dpp v90, v90, v90 quad_perm:[2,3,0,1] row_mask:0xf bank_mask:0xf bound_ctrl:1
	v_add_f32_dpp v91, v91, v91 quad_perm:[2,3,0,1] row_mask:0xf bank_mask:0xf bound_ctrl:1
	s_nop 0
	v_add_f32_dpp v90, v90, v90 row_half_mirror row_mask:0xf bank_mask:0xf bound_ctrl:1
	v_add_f32_dpp v91, v91, v91 row_half_mirror row_mask:0xf bank_mask:0xf bound_ctrl:1
	s_nop 0
	v_add_f32_dpp v90, v90, v90 row_mirror row_mask:0xf bank_mask:0xf bound_ctrl:1
	v_add_f32_dpp v91, v91, v91 row_mirror row_mask:0xf bank_mask:0xf bound_ctrl:1
	s_waitcnt lgkmcnt(2)
	v_pk_mul_f32 v[0:1], v[0:1], v[16:17] op_sel_hi:[1,0]
	v_pk_mul_f32 v[2:3], v[2:3], v[16:17] op_sel:[0,1]
	v_pk_mul_f32 v[4:5], v[4:5], v[18:19] op_sel_hi:[1,0]
	v_pk_mul_f32 v[6:7], v[6:7], v[18:19] op_sel:[0,1]
	ds_read_b128 v[16:19], v83 offset:1024
	v_pk_fma_f32 v[0:1], v[88:89], v[28:29], v[0:1] op_sel_hi:[1,0,1]
	v_pk_fma_f32 v[2:3], v[88:89], v[28:29], v[2:3] op_sel:[0,1,0]
	v_pk_fma_f32 v[4:5], v[88:89], v[30:31], v[4:5] op_sel_hi:[1,0,1]
	v_pk_fma_f32 v[6:7], v[88:89], v[30:31], v[6:7] op_sel:[0,1,0]
	ds_read_b128 v[28:31], v83 offset:13312
	ds_read_b64 v[88:89], v104 offset:21504
	v_pk_fma_f32 v[0:1], v[90:91], v[24:25], v[0:1] op_sel_hi:[1,0,1] neg_lo:[1,0,0] neg_hi:[1,0,0]
	v_pk_fma_f32 v[2:3], v[90:91], v[24:25], v[2:3] op_sel:[0,1,0] neg_lo:[1,0,0] neg_hi:[1,0,0]
	v_pk_fma_f32 v[4:5], v[90:91], v[26:27], v[4:5] op_sel_hi:[1,0,1] neg_lo:[1,0,0] neg_hi:[1,0,0]
	v_pk_fma_f32 v[6:7], v[90:91], v[26:27], v[6:7] op_sel:[0,1,0] neg_lo:[1,0,0] neg_hi:[1,0,0]
	ds_read_b128 v[24:27], v83 offset:9216
	s_waitcnt lgkmcnt(4)
	v_pk_mul_f32 v[90:91], v[0:1], v[20:21] op_sel_hi:[1,0]
	v_pk_mul_f32 v[92:93], v[0:1], v[84:85] op_sel_hi:[1,0]
	v_pk_fma_f32 v[90:91], v[2:3], v[20:21], v[90:91] op_sel:[0,1,0]
	v_pk_fma_f32 v[92:93], v[2:3], v[84:85], v[92:93] op_sel:[0,1,0]
	v_pk_fma_f32 v[90:91], v[4:5], v[22:23], v[90:91] op_sel_hi:[1,0,1]
	v_pk_fma_f32 v[92:93], v[4:5], v[86:87], v[92:93] op_sel_hi:[1,0,1]
	v_pk_fma_f32 v[90:91], v[6:7], v[22:23], v[90:91] op_sel:[0,1,0]
	v_pk_fma_f32 v[14:15], v[6:7], v[86:87], v[92:93] op_sel:[0,1,0]
	ds_read_b128 v[20:23], v83 offset:5376
	ds_read_b128 v[84:87], v83 offset:17408
	v_add_f32_dpp v90, v90, v90 quad_perm:[1,0,3,2] row_mask:0xf bank_mask:0xf bound_ctrl:1
	v_add_f32_dpp v91, v91, v91 quad_perm:[1,0,3,2] row_mask:0xf bank_mask:0xf bound_ctrl:1
	v_add_f32_dpp v12, v12, v12 row_mirror row_mask:0xf bank_mask:0x3
	v_add_f32_dpp v90, v90, v90 quad_perm:[2,3,0,1] row_mask:0xf bank_mask:0xf bound_ctrl:1
	v_add_f32_dpp v91, v91, v91 quad_perm:[2,3,0,1] row_mask:0xf bank_mask:0xf bound_ctrl:1
	v_add_f32_dpp v13, v13, v13 row_mirror row_mask:0xf bank_mask:0x3
	v_add_f32_dpp v90, v90, v90 row_half_mirror row_mask:0xf bank_mask:0xf bound_ctrl:1
	v_add_f32_dpp v91, v91, v91 row_half_mirror row_mask:0xf bank_mask:0xf bound_ctrl:1
	v_add_f32_dpp v12, v14, v14 row_mirror row_mask:0xf bank_mask:0xc
	v_add_f32_dpp v90, v90, v90 row_mirror row_mask:0xf bank_mask:0xf bound_ctrl:1
	v_add_f32_dpp v91, v91, v91 row_mirror row_mask:0xf bank_mask:0xf bound_ctrl:1
	s_waitcnt lgkmcnt(2)
	v_pk_mul_f32 v[0:1], v[0:1], v[16:17] op_sel_hi:[1,0]
	v_pk_mul_f32 v[2:3], v[2:3], v[16:17] op_sel:[0,1]
	v_pk_mul_f32 v[4:5], v[4:5], v[18:19] op_sel_hi:[1,0]
	v_pk_mul_f32 v[6:7], v[6:7], v[18:19] op_sel:[0,1]
	ds_read_b128 v[16:19], v83 offset:1280
	v_pk_fma_f32 v[0:1], v[88:89], v[28:29], v[0:1] op_sel_hi:[1,0,1]
	v_pk_fma_f32 v[2:3], v[88:89], v[28:29], v[2:3] op_sel:[0,1,0]
	v_pk_fma_f32 v[4:5], v[88:89], v[30:31], v[4:5] op_sel_hi:[1,0,1]
	v_pk_fma_f32 v[6:7], v[88:89], v[30:31], v[6:7] op_sel:[0,1,0]
	ds_read_b128 v[28:31], v83 offset:13568
	ds_read_b64 v[88:89], v104 offset:21760
	v_pk_fma_f32 v[0:1], v[90:91], v[24:25], v[0:1] op_sel_hi:[1,0,1] neg_lo:[1,0,0] neg_hi:[1,0,0]
	v_pk_fma_f32 v[2:3], v[90:91], v[24:25], v[2:3] op_sel:[0,1,0] neg_lo:[1,0,0] neg_hi:[1,0,0]
	v_pk_fma_f32 v[4:5], v[90:91], v[26:27], v[4:5] op_sel_hi:[1,0,1] neg_lo:[1,0,0] neg_hi:[1,0,0]
	v_pk_fma_f32 v[6:7], v[90:91], v[26:27], v[6:7] op_sel:[0,1,0] neg_lo:[1,0,0] neg_hi:[1,0,0]
	ds_read_b128 v[24:27], v83 offset:9472
	v_add_f32_dpp v13, v15, v15 row_mirror row_mask:0xf bank_mask:0xc
	s_waitcnt lgkmcnt(4)
	v_pk_mul_f32 v[90:91], v[0:1], v[20:21] op_sel_hi:[1,0]
	v_pk_mul_f32 v[92:93], v[0:1], v[84:85] op_sel_hi:[1,0]
	v_pk_fma_f32 v[90:91], v[2:3], v[20:21], v[90:91] op_sel:[0,1,0]
	v_pk_fma_f32 v[92:93], v[2:3], v[84:85], v[92:93] op_sel:[0,1,0]
	v_pk_fma_f32 v[90:91], v[4:5], v[22:23], v[90:91] op_sel_hi:[1,0,1]
	v_pk_fma_f32 v[92:93], v[4:5], v[86:87], v[92:93] op_sel_hi:[1,0,1]
	v_pk_fma_f32 v[90:91], v[6:7], v[22:23], v[90:91] op_sel:[0,1,0]
	v_pk_fma_f32 v[70:71], v[6:7], v[86:87], v[92:93] op_sel:[0,1,0]
	ds_read_b128 v[20:23], v83 offset:5632
	ds_read_b128 v[84:87], v83 offset:17664
	v_add_f32_dpp v90, v90, v90 quad_perm:[1,0,3,2] row_mask:0xf bank_mask:0xf bound_ctrl:1
	v_add_f32_dpp v91, v91, v91 quad_perm:[1,0,3,2] row_mask:0xf bank_mask:0xf bound_ctrl:1
	v_add_f32_dpp v8, v8, v8 row_half_mirror row_mask:0xf bank_mask:0x5
	v_add_f32_dpp v90, v90, v90 quad_perm:[2,3,0,1] row_mask:0xf bank_mask:0xf bound_ctrl:1
	v_add_f32_dpp v91, v91, v91 quad_perm:[2,3,0,1] row_mask:0xf bank_mask:0xf bound_ctrl:1
	v_add_f32_dpp v9, v9, v9 row_half_mirror row_mask:0xf bank_mask:0x5
	v_add_f32_dpp v90, v90, v90 row_half_mirror row_mask:0xf bank_mask:0xf bound_ctrl:1
	v_add_f32_dpp v91, v91, v91 row_half_mirror row_mask:0xf bank_mask:0xf bound_ctrl:1
	v_add_f32_dpp v8, v12, v12 row_half_mirror row_mask:0xf bank_mask:0xa
	v_add_f32_dpp v90, v90, v90 row_mirror row_mask:0xf bank_mask:0xf bound_ctrl:1
	v_add_f32_dpp v91, v91, v91 row_mirror row_mask:0xf bank_mask:0xf bound_ctrl:1
	s_waitcnt lgkmcnt(2)
	v_pk_mul_f32 v[0:1], v[0:1], v[16:17] op_sel_hi:[1,0]
	v_pk_mul_f32 v[2:3], v[2:3], v[16:17] op_sel:[0,1]
	v_pk_mul_f32 v[4:5], v[4:5], v[18:19] op_sel_hi:[1,0]
	v_pk_mul_f32 v[6:7], v[6:7], v[18:19] op_sel:[0,1]
	ds_read_b128 v[16:19], v83 offset:1536
	v_pk_fma_f32 v[0:1], v[88:89], v[28:29], v[0:1] op_sel_hi:[1,0,1]
	v_pk_fma_f32 v[2:3], v[88:89], v[28:29], v[2:3] op_sel:[0,1,0]
	v_pk_fma_f32 v[4:5], v[88:89], v[30:31], v[4:5] op_sel_hi:[1,0,1]
	v_pk_fma_f32 v[6:7], v[88:89], v[30:31], v[6:7] op_sel:[0,1,0]
	ds_read_b128 v[28:31], v83 offset:13824
	ds_read_b64 v[88:89], v104 offset:22016
	v_pk_fma_f32 v[0:1], v[90:91], v[24:25], v[0:1] op_sel_hi:[1,0,1] neg_lo:[1,0,0] neg_hi:[1,0,0]
	v_pk_fma_f32 v[2:3], v[90:91], v[24:25], v[2:3] op_sel:[0,1,0] neg_lo:[1,0,0] neg_hi:[1,0,0]
	v_pk_fma_f32 v[4:5], v[90:91], v[26:27], v[4:5] op_sel_hi:[1,0,1] neg_lo:[1,0,0] neg_hi:[1,0,0]
	v_pk_fma_f32 v[6:7], v[90:91], v[26:27], v[6:7] op_sel:[0,1,0] neg_lo:[1,0,0] neg_hi:[1,0,0]
	ds_read_b128 v[24:27], v83 offset:9728
	v_add_f32_dpp v9, v13, v13 row_half_mirror row_mask:0xf bank_mask:0xa
	s_waitcnt lgkmcnt(4)
	v_pk_mul_f32 v[90:91], v[0:1], v[20:21] op_sel_hi:[1,0]
	v_pk_mul_f32 v[92:93], v[0:1], v[84:85] op_sel_hi:[1,0]
	v_pk_fma_f32 v[90:91], v[2:3], v[20:21], v[90:91] op_sel:[0,1,0]
	v_pk_fma_f32 v[92:93], v[2:3], v[84:85], v[92:93] op_sel:[0,1,0]
	v_pk_fma_f32 v[90:91], v[4:5], v[22:23], v[90:91] op_sel_hi:[1,0,1]
	v_pk_fma_f32 v[92:93], v[4:5], v[86:87], v[92:93] op_sel_hi:[1,0,1]
	v_pk_fma_f32 v[90:91], v[6:7], v[22:23], v[90:91] op_sel:[0,1,0]
	v_pk_fma_f32 v[72:73], v[6:7], v[86:87], v[92:93] op_sel:[0,1,0]
	ds_read_b128 v[20:23], v83 offset:5888
	ds_read_b128 v[84:87], v83 offset:17920
	v_add_f32_dpp v90, v90, v90 quad_perm:[1,0,3,2] row_mask:0xf bank_mask:0xf bound_ctrl:1
	v_add_f32_dpp v91, v91, v91 quad_perm:[1,0,3,2] row_mask:0xf bank_mask:0xf bound_ctrl:1
	v_add_f32_dpp v70, v70, v70 row_mirror row_mask:0xf bank_mask:0x3
	v_add_f32_dpp v90, v90, v90 quad_perm:[2,3,0,1] row_mask:0xf bank_mask:0xf bound_ctrl:1
	v_add_f32_dpp v91, v91, v91 quad_perm:[2,3,0,1] row_mask:0xf bank_mask:0xf bound_ctrl:1
	v_add_f32_dpp v71, v71, v71 row_mirror row_mask:0xf bank_mask:0x3
	v_add_f32_dpp v90, v90, v90 row_half_mirror row_mask:0xf bank_mask:0xf bound_ctrl:1
	v_add_f32_dpp v91, v91, v91 row_half_mirror row_mask:0xf bank_mask:0xf bound_ctrl:1
	v_add_f32_dpp v70, v72, v72 row_mirror row_mask:0xf bank_mask:0xc
	v_add_f32_dpp v90, v90, v90 row_mirror row_mask:0xf bank_mask:0xf bound_ctrl:1
	v_add_f32_dpp v91, v91, v91 row_mirror row_mask:0xf bank_mask:0xf bound_ctrl:1
	s_waitcnt lgkmcnt(2)
	v_pk_mul_f32 v[0:1], v[0:1], v[16:17] op_sel_hi:[1,0]
	v_pk_mul_f32 v[2:3], v[2:3], v[16:17] op_sel:[0,1]
	v_pk_mul_f32 v[4:5], v[4:5], v[18:19] op_sel_hi:[1,0]
	v_pk_mul_f32 v[6:7], v[6:7], v[18:19] op_sel:[0,1]
	ds_read_b128 v[16:19], v83 offset:1792
	v_pk_fma_f32 v[0:1], v[88:89], v[28:29], v[0:1] op_sel_hi:[1,0,1]
	v_pk_fma_f32 v[2:3], v[88:89], v[28:29], v[2:3] op_sel:[0,1,0]
	v_pk_fma_f32 v[4:5], v[88:89], v[30:31], v[4:5] op_sel_hi:[1,0,1]
	v_pk_fma_f32 v[6:7], v[88:89], v[30:31], v[6:7] op_sel:[0,1,0]
	ds_read_b128 v[28:31], v83 offset:14080
	ds_read_b64 v[88:89], v104 offset:22272
	v_pk_fma_f32 v[0:1], v[90:91], v[24:25], v[0:1] op_sel_hi:[1,0,1] neg_lo:[1,0,0] neg_hi:[1,0,0]
	v_pk_fma_f32 v[2:3], v[90:91], v[24:25], v[2:3] op_sel:[0,1,0] neg_lo:[1,0,0] neg_hi:[1,0,0]
	v_pk_fma_f32 v[4:5], v[90:91], v[26:27], v[4:5] op_sel_hi:[1,0,1] neg_lo:[1,0,0] neg_hi:[1,0,0]
	v_pk_fma_f32 v[6:7], v[90:91], v[26:27], v[6:7] op_sel:[0,1,0] neg_lo:[1,0,0] neg_hi:[1,0,0]
	ds_read_b128 v[24:27], v83 offset:9984
	v_add_f32_dpp v71, v73, v73 row_mirror row_mask:0xf bank_mask:0xc
	s_waitcnt lgkmcnt(4)
	v_pk_mul_f32 v[90:91], v[0:1], v[20:21] op_sel_hi:[1,0]
	v_pk_mul_f32 v[92:93], v[0:1], v[84:85] op_sel_hi:[1,0]
	v_pk_fma_f32 v[90:91], v[2:3], v[20:21], v[90:91] op_sel:[0,1,0]
	v_pk_fma_f32 v[92:93], v[2:3], v[84:85], v[92:93] op_sel:[0,1,0]
	v_pk_fma_f32 v[90:91], v[4:5], v[22:23], v[90:91] op_sel_hi:[1,0,1]
	v_pk_fma_f32 v[92:93], v[4:5], v[86:87], v[92:93] op_sel_hi:[1,0,1]
	v_pk_fma_f32 v[90:91], v[6:7], v[22:23], v[90:91] op_sel:[0,1,0]
	v_pk_fma_f32 v[94:95], v[6:7], v[86:87], v[92:93] op_sel:[0,1,0]
	ds_read_b128 v[20:23], v83 offset:6144
	ds_read_b128 v[84:87], v83 offset:18176
	v_add_f32_dpp v90, v90, v90 quad_perm:[1,0,3,2] row_mask:0xf bank_mask:0xf bound_ctrl:1
	v_add_f32_dpp v91, v91, v91 quad_perm:[1,0,3,2] row_mask:0xf bank_mask:0xf bound_ctrl:1
	s_nop 0
	v_add_f32_dpp v90, v90, v90 quad_perm:[2,3,0,1] row_mask:0xf bank_mask:0xf bound_ctrl:1
	v_add_f32_dpp v91, v91, v91 quad_perm:[2,3,0,1] row_mask:0xf bank_mask:0xf bound_ctrl:1
	s_nop 0
	v_add_f32_dpp v90, v90, v90 row_half_mirror row_mask:0xf bank_mask:0xf bound_ctrl:1
	v_add_f32_dpp v91, v91, v91 row_half_mirror row_mask:0xf bank_mask:0xf bound_ctrl:1
	s_nop 0
	v_add_f32_dpp v90, v90, v90 row_mirror row_mask:0xf bank_mask:0xf bound_ctrl:1
	v_add_f32_dpp v91, v91, v91 row_mirror row_mask:0xf bank_mask:0xf bound_ctrl:1
	s_waitcnt lgkmcnt(2)
	v_pk_mul_f32 v[0:1], v[0:1], v[16:17] op_sel_hi:[1,0]
	v_pk_mul_f32 v[2:3], v[2:3], v[16:17] op_sel:[0,1]
	v_pk_mul_f32 v[4:5], v[4:5], v[18:19] op_sel_hi:[1,0]
	v_pk_mul_f32 v[6:7], v[6:7], v[18:19] op_sel:[0,1]
	ds_read_b128 v[16:19], v83 offset:2048
	v_pk_fma_f32 v[0:1], v[88:89], v[28:29], v[0:1] op_sel_hi:[1,0,1]
	v_pk_fma_f32 v[2:3], v[88:89], v[28:29], v[2:3] op_sel:[0,1,0]
	v_pk_fma_f32 v[4:5], v[88:89], v[30:31], v[4:5] op_sel_hi:[1,0,1]
	v_pk_fma_f32 v[6:7], v[88:89], v[30:31], v[6:7] op_sel:[0,1,0]
	ds_read_b128 v[28:31], v83 offset:14336
	ds_read_b64 v[88:89], v104 offset:22528
	v_pk_fma_f32 v[0:1], v[90:91], v[24:25], v[0:1] op_sel_hi:[1,0,1] neg_lo:[1,0,0] neg_hi:[1,0,0]
	v_pk_fma_f32 v[2:3], v[90:91], v[24:25], v[2:3] op_sel:[0,1,0] neg_lo:[1,0,0] neg_hi:[1,0,0]
	v_pk_fma_f32 v[4:5], v[90:91], v[26:27], v[4:5] op_sel_hi:[1,0,1] neg_lo:[1,0,0] neg_hi:[1,0,0]
	v_pk_fma_f32 v[6:7], v[90:91], v[26:27], v[6:7] op_sel:[0,1,0] neg_lo:[1,0,0] neg_hi:[1,0,0]
	ds_read_b128 v[24:27], v83 offset:10240
	s_waitcnt lgkmcnt(4)
	v_pk_mul_f32 v[90:91], v[0:1], v[20:21] op_sel_hi:[1,0]
	v_pk_mul_f32 v[92:93], v[0:1], v[84:85] op_sel_hi:[1,0]
	v_pk_fma_f32 v[90:91], v[2:3], v[20:21], v[90:91] op_sel:[0,1,0]
	v_pk_fma_f32 v[92:93], v[2:3], v[84:85], v[92:93] op_sel:[0,1,0]
	v_pk_fma_f32 v[90:91], v[4:5], v[22:23], v[90:91] op_sel_hi:[1,0,1]
	v_pk_fma_f32 v[92:93], v[4:5], v[86:87], v[92:93] op_sel_hi:[1,0,1]
	v_pk_fma_f32 v[90:91], v[6:7], v[22:23], v[90:91] op_sel:[0,1,0]
	v_pk_fma_f32 v[96:97], v[6:7], v[86:87], v[92:93] op_sel:[0,1,0]
	ds_read_b128 v[20:23], v83 offset:6400
	ds_read_b128 v[84:87], v83 offset:18432
	v_add_f32_dpp v90, v90, v90 quad_perm:[1,0,3,2] row_mask:0xf bank_mask:0xf bound_ctrl:1
	v_add_f32_dpp v91, v91, v91 quad_perm:[1,0,3,2] row_mask:0xf bank_mask:0xf bound_ctrl:1
	v_add_f32_dpp v94, v94, v94 row_mirror row_mask:0xf bank_mask:0x3
	v_add_f32_dpp v90, v90, v90 quad_perm:[2,3,0,1] row_mask:0xf bank_mask:0xf bound_ctrl:1
	v_add_f32_dpp v91, v91, v91 quad_perm:[2,3,0,1] row_mask:0xf bank_mask:0xf bound_ctrl:1
	v_add_f32_dpp v95, v95, v95 row_mirror row_mask:0xf bank_mask:0x3
	v_add_f32_dpp v90, v90, v90 row_half_mirror row_mask:0xf bank_mask:0xf bound_ctrl:1
	v_add_f32_dpp v91, v91, v91 row_half_mirror row_mask:0xf bank_mask:0xf bound_ctrl:1
	v_add_f32_dpp v94, v96, v96 row_mirror row_mask:0xf bank_mask:0xc
	v_add_f32_dpp v90, v90, v90 row_mirror row_mask:0xf bank_mask:0xf bound_ctrl:1
	v_add_f32_dpp v91, v91, v91 row_mirror row_mask:0xf bank_mask:0xf bound_ctrl:1
	s_waitcnt lgkmcnt(2)
	v_pk_mul_f32 v[0:1], v[0:1], v[16:17] op_sel_hi:[1,0]
	v_pk_mul_f32 v[2:3], v[2:3], v[16:17] op_sel:[0,1]
	v_pk_mul_f32 v[4:5], v[4:5], v[18:19] op_sel_hi:[1,0]
	v_pk_mul_f32 v[6:7], v[6:7], v[18:19] op_sel:[0,1]
	ds_read_b128 v[16:19], v83 offset:2304
	v_pk_fma_f32 v[0:1], v[88:89], v[28:29], v[0:1] op_sel_hi:[1,0,1]
	v_pk_fma_f32 v[2:3], v[88:89], v[28:29], v[2:3] op_sel:[0,1,0]
	v_pk_fma_f32 v[4:5], v[88:89], v[30:31], v[4:5] op_sel_hi:[1,0,1]
	v_pk_fma_f32 v[6:7], v[88:89], v[30:31], v[6:7] op_sel:[0,1,0]
	ds_read_b128 v[28:31], v83 offset:14592
	ds_read_b64 v[88:89], v104 offset:22784
	v_pk_fma_f32 v[0:1], v[90:91], v[24:25], v[0:1] op_sel_hi:[1,0,1] neg_lo:[1,0,0] neg_hi:[1,0,0]
	v_pk_fma_f32 v[2:3], v[90:91], v[24:25], v[2:3] op_sel:[0,1,0] neg_lo:[1,0,0] neg_hi:[1,0,0]
	v_pk_fma_f32 v[4:5], v[90:91], v[26:27], v[4:5] op_sel_hi:[1,0,1] neg_lo:[1,0,0] neg_hi:[1,0,0]
	v_pk_fma_f32 v[6:7], v[90:91], v[26:27], v[6:7] op_sel:[0,1,0] neg_lo:[1,0,0] neg_hi:[1,0,0]
	ds_read_b128 v[24:27], v83 offset:10496
	v_add_f32_dpp v95, v97, v97 row_mirror row_mask:0xf bank_mask:0xc
	s_waitcnt lgkmcnt(4)
	v_pk_mul_f32 v[90:91], v[0:1], v[20:21] op_sel_hi:[1,0]
	v_pk_mul_f32 v[92:93], v[0:1], v[84:85] op_sel_hi:[1,0]
	v_pk_fma_f32 v[90:91], v[2:3], v[20:21], v[90:91] op_sel:[0,1,0]
	v_pk_fma_f32 v[92:93], v[2:3], v[84:85], v[92:93] op_sel:[0,1,0]
	v_pk_fma_f32 v[90:91], v[4:5], v[22:23], v[90:91] op_sel_hi:[1,0,1]
	v_pk_fma_f32 v[92:93], v[4:5], v[86:87], v[92:93] op_sel_hi:[1,0,1]
	v_pk_fma_f32 v[90:91], v[6:7], v[22:23], v[90:91] op_sel:[0,1,0]
	v_pk_fma_f32 v[98:99], v[6:7], v[86:87], v[92:93] op_sel:[0,1,0]
	ds_read_b128 v[20:23], v83 offset:6656
	ds_read_b128 v[84:87], v83 offset:18688
	v_add_f32_dpp v90, v90, v90 quad_perm:[1,0,3,2] row_mask:0xf bank_mask:0xf bound_ctrl:1
	v_add_f32_dpp v91, v91, v91 quad_perm:[1,0,3,2] row_mask:0xf bank_mask:0xf bound_ctrl:1
	v_add_f32_dpp v70, v70, v70 row_half_mirror row_mask:0xf bank_mask:0x5
	v_add_f32_dpp v90, v90, v90 quad_perm:[2,3,0,1] row_mask:0xf bank_mask:0xf bound_ctrl:1
	v_add_f32_dpp v91, v91, v91 quad_perm:[2,3,0,1] row_mask:0xf bank_mask:0xf bound_ctrl:1
	v_add_f32_dpp v71, v71, v71 row_half_mirror row_mask:0xf bank_mask:0x5
	v_add_f32_dpp v90, v90, v90 row_half_mirror row_mask:0xf bank_mask:0xf bound_ctrl:1
	v_add_f32_dpp v91, v91, v91 row_half_mirror row_mask:0xf bank_mask:0xf bound_ctrl:1
	v_add_f32_dpp v70, v94, v94 row_half_mirror row_mask:0xf bank_mask:0xa
	v_add_f32_dpp v90, v90, v90 row_mirror row_mask:0xf bank_mask:0xf bound_ctrl:1
	v_add_f32_dpp v91, v91, v91 row_mirror row_mask:0xf bank_mask:0xf bound_ctrl:1
	s_waitcnt lgkmcnt(2)
	v_pk_mul_f32 v[0:1], v[0:1], v[16:17] op_sel_hi:[1,0]
	v_pk_mul_f32 v[2:3], v[2:3], v[16:17] op_sel:[0,1]
	v_pk_mul_f32 v[4:5], v[4:5], v[18:19] op_sel_hi:[1,0]
	v_pk_mul_f32 v[6:7], v[6:7], v[18:19] op_sel:[0,1]
	ds_read_b128 v[16:19], v83 offset:2560
	v_pk_fma_f32 v[0:1], v[88:89], v[28:29], v[0:1] op_sel_hi:[1,0,1]
	v_pk_fma_f32 v[2:3], v[88:89], v[28:29], v[2:3] op_sel:[0,1,0]
	v_pk_fma_f32 v[4:5], v[88:89], v[30:31], v[4:5] op_sel_hi:[1,0,1]
	v_pk_fma_f32 v[6:7], v[88:89], v[30:31], v[6:7] op_sel:[0,1,0]
	ds_read_b128 v[28:31], v83 offset:14848
	ds_read_b64 v[88:89], v104 offset:23040
	v_pk_fma_f32 v[0:1], v[90:91], v[24:25], v[0:1] op_sel_hi:[1,0,1] neg_lo:[1,0,0] neg_hi:[1,0,0]
	v_pk_fma_f32 v[2:3], v[90:91], v[24:25], v[2:3] op_sel:[0,1,0] neg_lo:[1,0,0] neg_hi:[1,0,0]
	v_pk_fma_f32 v[4:5], v[90:91], v[26:27], v[4:5] op_sel_hi:[1,0,1] neg_lo:[1,0,0] neg_hi:[1,0,0]
	v_pk_fma_f32 v[6:7], v[90:91], v[26:27], v[6:7] op_sel:[0,1,0] neg_lo:[1,0,0] neg_hi:[1,0,0]
	ds_read_b128 v[24:27], v83 offset:10752
	v_add_f32_dpp v71, v95, v95 row_half_mirror row_mask:0xf bank_mask:0xa
	s_waitcnt lgkmcnt(4)
	v_pk_mul_f32 v[90:91], v[0:1], v[20:21] op_sel_hi:[1,0]
	v_pk_mul_f32 v[92:93], v[0:1], v[84:85] op_sel_hi:[1,0]
	v_pk_fma_f32 v[90:91], v[2:3], v[20:21], v[90:91] op_sel:[0,1,0]
	v_pk_fma_f32 v[92:93], v[2:3], v[84:85], v[92:93] op_sel:[0,1,0]
	v_pk_fma_f32 v[90:91], v[4:5], v[22:23], v[90:91] op_sel_hi:[1,0,1]
	v_pk_fma_f32 v[92:93], v[4:5], v[86:87], v[92:93] op_sel_hi:[1,0,1]
	v_pk_fma_f32 v[90:91], v[6:7], v[22:23], v[90:91] op_sel:[0,1,0]
	v_pk_fma_f32 v[100:101], v[6:7], v[86:87], v[92:93] op_sel:[0,1,0]
	ds_read_b128 v[20:23], v83 offset:6912
	ds_read_b128 v[84:87], v83 offset:18944
	v_add_f32_dpp v90, v90, v90 quad_perm:[1,0,3,2] row_mask:0xf bank_mask:0xf bound_ctrl:1
	v_add_f32_dpp v91, v91, v91 quad_perm:[1,0,3,2] row_mask:0xf bank_mask:0xf bound_ctrl:1
	v_add_f32_dpp v98, v98, v98 row_mirror row_mask:0xf bank_mask:0x3
	v_add_f32_dpp v90, v90, v90 quad_perm:[2,3,0,1] row_mask:0xf bank_mask:0xf bound_ctrl:1
	v_add_f32_dpp v91, v91, v91 quad_perm:[2,3,0,1] row_mask:0xf bank_mask:0xf bound_ctrl:1
	v_add_f32_dpp v99, v99, v99 row_mirror row_mask:0xf bank_mask:0x3
	v_add_f32_dpp v90, v90, v90 row_half_mirror row_mask:0xf bank_mask:0xf bound_ctrl:1
	v_add_f32_dpp v91, v91, v91 row_half_mirror row_mask:0xf bank_mask:0xf bound_ctrl:1
	v_add_f32_dpp v98, v100, v100 row_mirror row_mask:0xf bank_mask:0xc
	v_add_f32_dpp v90, v90, v90 row_mirror row_mask:0xf bank_mask:0xf bound_ctrl:1
	v_add_f32_dpp v91, v91, v91 row_mirror row_mask:0xf bank_mask:0xf bound_ctrl:1
	s_waitcnt lgkmcnt(2)
	v_pk_mul_f32 v[0:1], v[0:1], v[16:17] op_sel_hi:[1,0]
	v_pk_mul_f32 v[2:3], v[2:3], v[16:17] op_sel:[0,1]
	v_pk_mul_f32 v[4:5], v[4:5], v[18:19] op_sel_hi:[1,0]
	v_pk_mul_f32 v[6:7], v[6:7], v[18:19] op_sel:[0,1]
	ds_read_b128 v[16:19], v83 offset:2816
	v_pk_fma_f32 v[0:1], v[88:89], v[28:29], v[0:1] op_sel_hi:[1,0,1]
	v_pk_fma_f32 v[2:3], v[88:89], v[28:29], v[2:3] op_sel:[0,1,0]
	v_pk_fma_f32 v[4:5], v[88:89], v[30:31], v[4:5] op_sel_hi:[1,0,1]
	v_pk_fma_f32 v[6:7], v[88:89], v[30:31], v[6:7] op_sel:[0,1,0]
	ds_read_b128 v[28:31], v83 offset:15104
	ds_read_b64 v[88:89], v104 offset:23296
	v_pk_fma_f32 v[0:1], v[90:91], v[24:25], v[0:1] op_sel_hi:[1,0,1] neg_lo:[1,0,0] neg_hi:[1,0,0]
	v_pk_fma_f32 v[2:3], v[90:91], v[24:25], v[2:3] op_sel:[0,1,0] neg_lo:[1,0,0] neg_hi:[1,0,0]
	v_pk_fma_f32 v[4:5], v[90:91], v[26:27], v[4:5] op_sel_hi:[1,0,1] neg_lo:[1,0,0] neg_hi:[1,0,0]
	v_pk_fma_f32 v[6:7], v[90:91], v[26:27], v[6:7] op_sel:[0,1,0] neg_lo:[1,0,0] neg_hi:[1,0,0]
	ds_read_b128 v[24:27], v83 offset:11008
	v_add_f32_dpp v99, v101, v101 row_mirror row_mask:0xf bank_mask:0xc
	s_waitcnt lgkmcnt(4)
	v_pk_mul_f32 v[90:91], v[0:1], v[20:21] op_sel_hi:[1,0]
	v_pk_mul_f32 v[92:93], v[0:1], v[84:85] op_sel_hi:[1,0]
	v_pk_fma_f32 v[90:91], v[2:3], v[20:21], v[90:91] op_sel:[0,1,0]
	v_pk_fma_f32 v[92:93], v[2:3], v[84:85], v[92:93] op_sel:[0,1,0]
	v_pk_fma_f32 v[90:91], v[4:5], v[22:23], v[90:91] op_sel_hi:[1,0,1]
	v_pk_fma_f32 v[92:93], v[4:5], v[86:87], v[92:93] op_sel_hi:[1,0,1]
	v_pk_fma_f32 v[90:91], v[6:7], v[22:23], v[90:91] op_sel:[0,1,0]
	v_pk_fma_f32 v[102:103], v[6:7], v[86:87], v[92:93] op_sel:[0,1,0]
	ds_read_b128 v[20:23], v83 offset:7168
	ds_read_b128 v[84:87], v83 offset:19200
	v_add_f32_dpp v90, v90, v90 quad_perm:[1,0,3,2] row_mask:0xf bank_mask:0xf bound_ctrl:1
	v_add_f32_dpp v91, v91, v91 quad_perm:[1,0,3,2] row_mask:0xf bank_mask:0xf bound_ctrl:1
	v_add_f32_dpp v8, v8, v8 quad_perm:[2,3,0,1] row_mask:0xf bank_mask:0xf bound_ctrl:1
	v_add_f32_dpp v90, v90, v90 quad_perm:[2,3,0,1] row_mask:0xf bank_mask:0xf bound_ctrl:1
	v_add_f32_dpp v91, v91, v91 quad_perm:[2,3,0,1] row_mask:0xf bank_mask:0xf bound_ctrl:1
	v_add_f32_dpp v70, v70, v70 quad_perm:[2,3,0,1] row_mask:0xf bank_mask:0xf bound_ctrl:1
	v_add_f32_dpp v90, v90, v90 row_half_mirror row_mask:0xf bank_mask:0xf bound_ctrl:1
	v_add_f32_dpp v91, v91, v91 row_half_mirror row_mask:0xf bank_mask:0xf bound_ctrl:1
	v_add_f32_dpp v9, v9, v9 quad_perm:[2,3,0,1] row_mask:0xf bank_mask:0xf bound_ctrl:1
	v_add_f32_dpp v90, v90, v90 row_mirror row_mask:0xf bank_mask:0xf bound_ctrl:1
	v_add_f32_dpp v91, v91, v91 row_mirror row_mask:0xf bank_mask:0xf bound_ctrl:1
	s_waitcnt lgkmcnt(2)
	v_pk_mul_f32 v[0:1], v[0:1], v[16:17] op_sel_hi:[1,0]
	v_pk_mul_f32 v[2:3], v[2:3], v[16:17] op_sel:[0,1]
	v_pk_mul_f32 v[4:5], v[4:5], v[18:19] op_sel_hi:[1,0]
	v_pk_mul_f32 v[6:7], v[6:7], v[18:19] op_sel:[0,1]
	ds_read_b128 v[16:19], v83 offset:3072
	v_pk_fma_f32 v[0:1], v[88:89], v[28:29], v[0:1] op_sel_hi:[1,0,1]
	v_pk_fma_f32 v[2:3], v[88:89], v[28:29], v[2:3] op_sel:[0,1,0]
	v_pk_fma_f32 v[4:5], v[88:89], v[30:31], v[4:5] op_sel_hi:[1,0,1]
	v_pk_fma_f32 v[6:7], v[88:89], v[30:31], v[6:7] op_sel:[0,1,0]
	ds_read_b128 v[28:31], v83 offset:15360
	ds_read_b64 v[88:89], v104 offset:23552
	v_pk_fma_f32 v[0:1], v[90:91], v[24:25], v[0:1] op_sel_hi:[1,0,1] neg_lo:[1,0,0] neg_hi:[1,0,0]
	v_pk_fma_f32 v[2:3], v[90:91], v[24:25], v[2:3] op_sel:[0,1,0] neg_lo:[1,0,0] neg_hi:[1,0,0]
	v_pk_fma_f32 v[4:5], v[90:91], v[26:27], v[4:5] op_sel_hi:[1,0,1] neg_lo:[1,0,0] neg_hi:[1,0,0]
	v_pk_fma_f32 v[6:7], v[90:91], v[26:27], v[6:7] op_sel:[0,1,0] neg_lo:[1,0,0] neg_hi:[1,0,0]
	ds_read_b128 v[24:27], v83 offset:11264
	v_add_f32_dpp v71, v71, v71 quad_perm:[2,3,0,1] row_mask:0xf bank_mask:0xf bound_ctrl:1
	s_waitcnt lgkmcnt(4)
	v_pk_mul_f32 v[90:91], v[0:1], v[20:21] op_sel_hi:[1,0]
	v_pk_mul_f32 v[92:93], v[0:1], v[84:85] op_sel_hi:[1,0]
	v_pk_fma_f32 v[90:91], v[2:3], v[20:21], v[90:91] op_sel:[0,1,0]
	v_pk_fma_f32 v[92:93], v[2:3], v[84:85], v[92:93] op_sel:[0,1,0]
	v_pk_fma_f32 v[90:91], v[4:5], v[22:23], v[90:91] op_sel_hi:[1,0,1]
	v_pk_fma_f32 v[92:93], v[4:5], v[86:87], v[92:93] op_sel_hi:[1,0,1]
	v_pk_fma_f32 v[90:91], v[6:7], v[22:23], v[90:91] op_sel:[0,1,0]
	v_pk_fma_f32 v[10:11], v[6:7], v[86:87], v[92:93] op_sel:[0,1,0]
	ds_read_b128 v[20:23], v83 offset:7424
	ds_read_b128 v[84:87], v83 offset:19456
	v_add_f32_dpp v90, v90, v90 quad_perm:[1,0,3,2] row_mask:0xf bank_mask:0xf bound_ctrl:1
	v_add_f32_dpp v91, v91, v91 quad_perm:[1,0,3,2] row_mask:0xf bank_mask:0xf bound_ctrl:1
	v_add_f32_dpp v102, v102, v102 row_mirror row_mask:0xf bank_mask:0x3
	v_add_f32_dpp v90, v90, v90 quad_perm:[2,3,0,1] row_mask:0xf bank_mask:0xf bound_ctrl:1
	v_add_f32_dpp v91, v91, v91 quad_perm:[2,3,0,1] row_mask:0xf bank_mask:0xf bound_ctrl:1
	v_add_f32_dpp v103, v103, v103 row_mirror row_mask:0xf bank_mask:0x3
	v_add_f32_dpp v90, v90, v90 row_half_mirror row_mask:0xf bank_mask:0xf bound_ctrl:1
	v_add_f32_dpp v91, v91, v91 row_half_mirror row_mask:0xf bank_mask:0xf bound_ctrl:1
	v_add_f32_dpp v102, v10, v10 row_mirror row_mask:0xf bank_mask:0xc
	v_add_f32_dpp v90, v90, v90 row_mirror row_mask:0xf bank_mask:0xf bound_ctrl:1
	v_add_f32_dpp v91, v91, v91 row_mirror row_mask:0xf bank_mask:0xf bound_ctrl:1
	s_waitcnt lgkmcnt(2)
	v_pk_mul_f32 v[0:1], v[0:1], v[16:17] op_sel_hi:[1,0]
	v_pk_mul_f32 v[2:3], v[2:3], v[16:17] op_sel:[0,1]
	v_pk_mul_f32 v[4:5], v[4:5], v[18:19] op_sel_hi:[1,0]
	v_pk_mul_f32 v[6:7], v[6:7], v[18:19] op_sel:[0,1]
	ds_read_b128 v[16:19], v83 offset:3328
	v_pk_fma_f32 v[0:1], v[88:89], v[28:29], v[0:1] op_sel_hi:[1,0,1]
	v_pk_fma_f32 v[2:3], v[88:89], v[28:29], v[2:3] op_sel:[0,1,0]
	v_pk_fma_f32 v[4:5], v[88:89], v[30:31], v[4:5] op_sel_hi:[1,0,1]
	v_pk_fma_f32 v[6:7], v[88:89], v[30:31], v[6:7] op_sel:[0,1,0]
	ds_read_b128 v[28:31], v83 offset:15616
	ds_read_b64 v[88:89], v104 offset:23808
	v_pk_fma_f32 v[0:1], v[90:91], v[24:25], v[0:1] op_sel_hi:[1,0,1] neg_lo:[1,0,0] neg_hi:[1,0,0]
	v_pk_fma_f32 v[2:3], v[90:91], v[24:25], v[2:3] op_sel:[0,1,0] neg_lo:[1,0,0] neg_hi:[1,0,0]
	v_pk_fma_f32 v[4:5], v[90:91], v[26:27], v[4:5] op_sel_hi:[1,0,1] neg_lo:[1,0,0] neg_hi:[1,0,0]
	v_pk_fma_f32 v[6:7], v[90:91], v[26:27], v[6:7] op_sel:[0,1,0] neg_lo:[1,0,0] neg_hi:[1,0,0]
	ds_read_b128 v[24:27], v83 offset:11520
	v_add_f32_dpp v103, v11, v11 row_mirror row_mask:0xf bank_mask:0xc
	s_waitcnt lgkmcnt(4)
	v_pk_mul_f32 v[90:91], v[0:1], v[20:21] op_sel_hi:[1,0]
	v_pk_mul_f32 v[92:93], v[0:1], v[84:85] op_sel_hi:[1,0]
	v_pk_fma_f32 v[90:91], v[2:3], v[20:21], v[90:91] op_sel:[0,1,0]
	v_pk_fma_f32 v[92:93], v[2:3], v[84:85], v[92:93] op_sel:[0,1,0]
	v_pk_fma_f32 v[90:91], v[4:5], v[22:23], v[90:91] op_sel_hi:[1,0,1]
	v_pk_fma_f32 v[92:93], v[4:5], v[86:87], v[92:93] op_sel_hi:[1,0,1]
	v_pk_fma_f32 v[90:91], v[6:7], v[22:23], v[90:91] op_sel:[0,1,0]
	v_pk_fma_f32 v[14:15], v[6:7], v[86:87], v[92:93] op_sel:[0,1,0]
	ds_read_b128 v[20:23], v83 offset:7680
	ds_read_b128 v[84:87], v83 offset:19712
	v_add_f32_dpp v90, v90, v90 quad_perm:[1,0,3,2] row_mask:0xf bank_mask:0xf bound_ctrl:1
	v_add_f32_dpp v91, v91, v91 quad_perm:[1,0,3,2] row_mask:0xf bank_mask:0xf bound_ctrl:1
	v_add_f32_dpp v98, v98, v98 row_half_mirror row_mask:0xf bank_mask:0x5
	v_add_f32_dpp v90, v90, v90 quad_perm:[2,3,0,1] row_mask:0xf bank_mask:0xf bound_ctrl:1
	v_add_f32_dpp v91, v91, v91 quad_perm:[2,3,0,1] row_mask:0xf bank_mask:0xf bound_ctrl:1
	v_add_f32_dpp v99, v99, v99 row_half_mirror row_mask:0xf bank_mask:0x5
	v_add_f32_dpp v90, v90, v90 row_half_mirror row_mask:0xf bank_mask:0xf bound_ctrl:1
	v_add_f32_dpp v91, v91, v91 row_half_mirror row_mask:0xf bank_mask:0xf bound_ctrl:1
	v_add_f32_dpp v98, v102, v102 row_half_mirror row_mask:0xf bank_mask:0xa
	v_add_f32_dpp v90, v90, v90 row_mirror row_mask:0xf bank_mask:0xf bound_ctrl:1
	v_add_f32_dpp v91, v91, v91 row_mirror row_mask:0xf bank_mask:0xf bound_ctrl:1
	s_waitcnt lgkmcnt(2)
	v_pk_mul_f32 v[0:1], v[0:1], v[16:17] op_sel_hi:[1,0]
	v_pk_mul_f32 v[2:3], v[2:3], v[16:17] op_sel:[0,1]
	v_pk_mul_f32 v[4:5], v[4:5], v[18:19] op_sel_hi:[1,0]
	v_pk_mul_f32 v[6:7], v[6:7], v[18:19] op_sel:[0,1]
	ds_read_b128 v[16:19], v83 offset:3584
	v_pk_fma_f32 v[0:1], v[88:89], v[28:29], v[0:1] op_sel_hi:[1,0,1]
	v_pk_fma_f32 v[2:3], v[88:89], v[28:29], v[2:3] op_sel:[0,1,0]
	v_pk_fma_f32 v[4:5], v[88:89], v[30:31], v[4:5] op_sel_hi:[1,0,1]
	v_pk_fma_f32 v[6:7], v[88:89], v[30:31], v[6:7] op_sel:[0,1,0]
	ds_read_b128 v[28:31], v83 offset:15872
	ds_read_b64 v[88:89], v104 offset:24064
	v_pk_fma_f32 v[0:1], v[90:91], v[24:25], v[0:1] op_sel_hi:[1,0,1] neg_lo:[1,0,0] neg_hi:[1,0,0]
	v_pk_fma_f32 v[2:3], v[90:91], v[24:25], v[2:3] op_sel:[0,1,0] neg_lo:[1,0,0] neg_hi:[1,0,0]
	v_pk_fma_f32 v[4:5], v[90:91], v[26:27], v[4:5] op_sel_hi:[1,0,1] neg_lo:[1,0,0] neg_hi:[1,0,0]
	v_pk_fma_f32 v[6:7], v[90:91], v[26:27], v[6:7] op_sel:[0,1,0] neg_lo:[1,0,0] neg_hi:[1,0,0]
	ds_read_b128 v[24:27], v83 offset:11776
	v_add_f32_dpp v99, v103, v103 row_half_mirror row_mask:0xf bank_mask:0xa
	s_waitcnt lgkmcnt(4)
	v_pk_mul_f32 v[90:91], v[0:1], v[20:21] op_sel_hi:[1,0]
	v_pk_mul_f32 v[92:93], v[0:1], v[84:85] op_sel_hi:[1,0]
	v_pk_fma_f32 v[90:91], v[2:3], v[20:21], v[90:91] op_sel:[0,1,0]
	v_pk_fma_f32 v[92:93], v[2:3], v[84:85], v[92:93] op_sel:[0,1,0]
	v_pk_fma_f32 v[90:91], v[4:5], v[22:23], v[90:91] op_sel_hi:[1,0,1]
	v_pk_fma_f32 v[92:93], v[4:5], v[86:87], v[92:93] op_sel_hi:[1,0,1]
	v_pk_fma_f32 v[90:91], v[6:7], v[22:23], v[90:91] op_sel:[0,1,0]
	v_pk_fma_f32 v[12:13], v[6:7], v[86:87], v[92:93] op_sel:[0,1,0]
	ds_read_b128 v[20:23], v83 offset:7936
	ds_read_b128 v[84:87], v83 offset:19968
	v_add_f32_dpp v90, v90, v90 quad_perm:[1,0,3,2] row_mask:0xf bank_mask:0xf bound_ctrl:1
	v_add_f32_dpp v91, v91, v91 quad_perm:[1,0,3,2] row_mask:0xf bank_mask:0xf bound_ctrl:1
	v_add_f32_dpp v14, v14, v14 row_mirror row_mask:0xf bank_mask:0x3
	v_add_f32_dpp v90, v90, v90 quad_perm:[2,3,0,1] row_mask:0xf bank_mask:0xf bound_ctrl:1
	v_add_f32_dpp v91, v91, v91 quad_perm:[2,3,0,1] row_mask:0xf bank_mask:0xf bound_ctrl:1
	v_add_f32_dpp v15, v15, v15 row_mirror row_mask:0xf bank_mask:0x3
	v_add_f32_dpp v90, v90, v90 row_half_mirror row_mask:0xf bank_mask:0xf bound_ctrl:1
	v_add_f32_dpp v91, v91, v91 row_half_mirror row_mask:0xf bank_mask:0xf bound_ctrl:1
	v_add_f32_dpp v14, v12, v12 row_mirror row_mask:0xf bank_mask:0xc
	v_add_f32_dpp v90, v90, v90 row_mirror row_mask:0xf bank_mask:0xf bound_ctrl:1
	v_add_f32_dpp v91, v91, v91 row_mirror row_mask:0xf bank_mask:0xf bound_ctrl:1
	s_waitcnt lgkmcnt(2)
	v_pk_mul_f32 v[0:1], v[0:1], v[16:17] op_sel_hi:[1,0]
	v_pk_mul_f32 v[2:3], v[2:3], v[16:17] op_sel:[0,1]
	v_pk_mul_f32 v[4:5], v[4:5], v[18:19] op_sel_hi:[1,0]
	v_pk_mul_f32 v[6:7], v[6:7], v[18:19] op_sel:[0,1]
	ds_read_b128 v[16:19], v83 offset:3840
	v_pk_fma_f32 v[0:1], v[88:89], v[28:29], v[0:1] op_sel_hi:[1,0,1]
	v_pk_fma_f32 v[2:3], v[88:89], v[28:29], v[2:3] op_sel:[0,1,0]
	v_pk_fma_f32 v[4:5], v[88:89], v[30:31], v[4:5] op_sel_hi:[1,0,1]
	v_pk_fma_f32 v[6:7], v[88:89], v[30:31], v[6:7] op_sel:[0,1,0]
	ds_read_b128 v[28:31], v83 offset:16128
	ds_read_b64 v[88:89], v104 offset:24320
	v_pk_fma_f32 v[0:1], v[90:91], v[24:25], v[0:1] op_sel_hi:[1,0,1] neg_lo:[1,0,0] neg_hi:[1,0,0]
	v_pk_fma_f32 v[2:3], v[90:91], v[24:25], v[2:3] op_sel:[0,1,0] neg_lo:[1,0,0] neg_hi:[1,0,0]
	v_pk_fma_f32 v[4:5], v[90:91], v[26:27], v[4:5] op_sel_hi:[1,0,1] neg_lo:[1,0,0] neg_hi:[1,0,0]
	v_pk_fma_f32 v[6:7], v[90:91], v[26:27], v[6:7] op_sel:[0,1,0] neg_lo:[1,0,0] neg_hi:[1,0,0]
	ds_read_b128 v[24:27], v83 offset:12032
	v_add_f32_dpp v15, v13, v13 row_mirror row_mask:0xf bank_mask:0xc
	s_waitcnt lgkmcnt(4)
	v_pk_mul_f32 v[90:91], v[0:1], v[20:21] op_sel_hi:[1,0]
	v_pk_mul_f32 v[92:93], v[0:1], v[84:85] op_sel_hi:[1,0]
	v_pk_fma_f32 v[90:91], v[2:3], v[20:21], v[90:91] op_sel:[0,1,0]
	v_pk_fma_f32 v[92:93], v[2:3], v[84:85], v[92:93] op_sel:[0,1,0]
	v_pk_fma_f32 v[90:91], v[4:5], v[22:23], v[90:91] op_sel_hi:[1,0,1]
	v_pk_fma_f32 v[92:93], v[4:5], v[86:87], v[92:93] op_sel_hi:[1,0,1]
	v_pk_fma_f32 v[90:91], v[6:7], v[22:23], v[90:91] op_sel:[0,1,0]
	v_pk_fma_f32 v[72:73], v[6:7], v[86:87], v[92:93] op_sel:[0,1,0]
	ds_read_b128 v[84:87], v83 offset:20224
	v_add_f32_dpp v90, v90, v90 quad_perm:[1,0,3,2] row_mask:0xf bank_mask:0xf bound_ctrl:1
	v_add_f32_dpp v91, v91, v91 quad_perm:[1,0,3,2] row_mask:0xf bank_mask:0xf bound_ctrl:1
	v_cndmask_b32_e64 v8, v8, v70, s[46:47]
	v_add_f32_dpp v90, v90, v90 quad_perm:[2,3,0,1] row_mask:0xf bank_mask:0xf bound_ctrl:1
	v_add_f32_dpp v91, v91, v91 quad_perm:[2,3,0,1] row_mask:0xf bank_mask:0xf bound_ctrl:1
	v_cndmask_b32_e64 v9, v9, v71, s[46:47]
	v_add_f32_dpp v90, v90, v90 row_half_mirror row_mask:0xf bank_mask:0xf bound_ctrl:1
	v_add_f32_dpp v91, v91, v91 row_half_mirror row_mask:0xf bank_mask:0xf bound_ctrl:1
	s_nop 0
	v_add_f32_dpp v90, v90, v90 row_mirror row_mask:0xf bank_mask:0xf bound_ctrl:1
	v_add_f32_dpp v91, v91, v91 row_mirror row_mask:0xf bank_mask:0xf bound_ctrl:1
	s_waitcnt lgkmcnt(1)
	v_pk_mul_f32 v[0:1], v[0:1], v[16:17] op_sel_hi:[1,0]
	v_pk_mul_f32 v[2:3], v[2:3], v[16:17] op_sel:[0,1]
	v_pk_mul_f32 v[4:5], v[4:5], v[18:19] op_sel_hi:[1,0]
	v_pk_mul_f32 v[6:7], v[6:7], v[18:19] op_sel:[0,1]
	v_pk_fma_f32 v[0:1], v[88:89], v[28:29], v[0:1] op_sel_hi:[1,0,1]
	v_pk_fma_f32 v[2:3], v[88:89], v[28:29], v[2:3] op_sel:[0,1,0]
	v_pk_fma_f32 v[4:5], v[88:89], v[30:31], v[4:5] op_sel_hi:[1,0,1]
	v_pk_fma_f32 v[6:7], v[88:89], v[30:31], v[6:7] op_sel:[0,1,0]
	v_pk_fma_f32 v[0:1], v[90:91], v[24:25], v[0:1] op_sel_hi:[1,0,1] neg_lo:[1,0,0] neg_hi:[1,0,0]
	v_pk_fma_f32 v[2:3], v[90:91], v[24:25], v[2:3] op_sel:[0,1,0] neg_lo:[1,0,0] neg_hi:[1,0,0]
	v_pk_fma_f32 v[4:5], v[90:91], v[26:27], v[4:5] op_sel_hi:[1,0,1] neg_lo:[1,0,0] neg_hi:[1,0,0]
	v_pk_fma_f32 v[6:7], v[90:91], v[26:27], v[6:7] op_sel:[0,1,0] neg_lo:[1,0,0] neg_hi:[1,0,0]
	s_waitcnt lgkmcnt(0)
	v_pk_mul_f32 v[92:93], v[0:1], v[84:85] op_sel_hi:[1,0]
	v_pk_fma_f32 v[92:93], v[2:3], v[84:85], v[92:93] op_sel:[0,1,0]
	v_pk_fma_f32 v[92:93], v[4:5], v[86:87], v[92:93] op_sel_hi:[1,0,1]
	v_pk_fma_f32 v[96:97], v[6:7], v[86:87], v[92:93] op_sel:[0,1,0]
	v_bfrev_b32_e32 v105, v33
	v_lshrrev_b32_e32 v105, 28, v105
	v_add_f32_dpp v72, v72, v72 row_mirror row_mask:0xf bank_mask:0x3
	v_add_f32_dpp v73, v73, v73 row_mirror row_mask:0xf bank_mask:0x3
	v_add_f32_dpp v72, v96, v96 row_mirror row_mask:0xf bank_mask:0xc
	v_add_f32_dpp v73, v97, v97 row_mirror row_mask:0xf bank_mask:0xc
	v_add_f32_dpp v14, v14, v14 row_half_mirror row_mask:0xf bank_mask:0x5
	v_add_f32_dpp v15, v15, v15 row_half_mirror row_mask:0xf bank_mask:0x5
	v_add_f32_dpp v14, v72, v72 row_half_mirror row_mask:0xf bank_mask:0xa
	v_add_f32_dpp v15, v73, v73 row_half_mirror row_mask:0xf bank_mask:0xa
	v_add_f32_dpp v98, v98, v98 quad_perm:[2,3,0,1] row_mask:0xf bank_mask:0xf bound_ctrl:1
	v_add_f32_dpp v14, v14, v14 quad_perm:[2,3,0,1] row_mask:0xf bank_mask:0xf bound_ctrl:1
	v_add_f32_dpp v99, v99, v99 quad_perm:[2,3,0,1] row_mask:0xf bank_mask:0xf bound_ctrl:1
	v_add_f32_dpp v15, v15, v15 quad_perm:[2,3,0,1] row_mask:0xf bank_mask:0xf bound_ctrl:1
	v_cndmask_b32_e64 v98, v98, v14, s[46:47]
	v_cndmask_b32_e64 v99, v99, v15, s[46:47]
	v_add_u32_e32 v105, s83, v105
	v_add_u32_e32 v105, s26, v105
	v_add_f32_dpp v8, v8, v8 quad_perm:[1,0,3,2] row_mask:0xf bank_mask:0xf bound_ctrl:1
	v_add_f32_dpp v98, v98, v98 quad_perm:[1,0,3,2] row_mask:0xf bank_mask:0xf bound_ctrl:1
	v_add_f32_dpp v9, v9, v9 quad_perm:[1,0,3,2] row_mask:0xf bank_mask:0xf bound_ctrl:1
	v_add_f32_dpp v99, v99, v99 quad_perm:[1,0,3,2] row_mask:0xf bank_mask:0xf bound_ctrl:1
	v_cndmask_b32_e64 v8, v8, v98, s[44:45]
	v_cndmask_b32_e64 v9, v9, v99, s[44:45]
	v_lshlrev_b32_e32 v104, 12, v105
	v_mov_b32_e32 v105, 0
	v_lshl_add_u64 v[104:105], v[64:65], 0, v[104:105]
	global_store_dwordx2 v[104:105], v[8:9], off
	s_branch .LBB0_4107
.LBB0_4119:
	s_and_b64 s[12:13], s[12:13], s[42:43]
	s_and_saveexec_b64 s[4:5], s[12:13]
	s_cbranch_execz .LBB0_4098
	s_lshl_b32 s12, s14, 4
	s_or_b32 s12, s12, s27
	s_ashr_i32 s13, s12, 31
	s_lshl_b64 s[12:13], s[12:13], 14
	v_readlane_b32 s14, v252, 26
	s_add_u32 s12, s14, s12
	v_readlane_b32 s14, v252, 27
	s_addc_u32 s13, s14, s13
	v_lshlrev_b32_e32 v8, 2, v52
	v_mov_b32_e32 v9, v81
	v_lshl_add_u64 v[8:9], s[12:13], 0, v[8:9]
	v_lshl_add_u64 v[8:9], v[8:9], 0, v[80:81]
	v_mov_b32_e32 v10, v0
	v_mov_b32_e32 v11, v2
	v_mov_b32_e32 v12, v4
	v_mov_b32_e32 v13, v6
	v_mov_b32_e32 v14, v1
	v_mov_b32_e32 v15, v3
	v_mov_b32_e32 v16, v5
	v_mov_b32_e32 v17, v7
	global_store_dwordx4 v[8:9], v[10:13], off
	global_store_dwordx4 v[8:9], v[14:17], off offset:256
	s_branch .LBB0_4098
